# v12 + lazy-rescale diff attention (row max only computed in the rare redo path; trigger = lane row-sum > 256)
# speedup vs baseline: 1.0218x; 1.0076x over previous
; template <int DQ, bool NA, int NQG>
; DI void attn_wg(const half_t* Qp, const half_t* Kp, const half_t* Vp, int q0, bool active, int seg0_start, int seg0_tiles,
;                 int seg1_start, int seg1_tiles, const float* rpb_h, int rq, char* smem, int tid, f16v (&O)[2][NQG]) {
;     ...
;       for (int st = 0; st < 2; ++st) {
;         f16v S[NQG];
; #pragma unroll
;         for (int qg = 0; qg < NQG; ++qg)
; #pragma unroll
;           for (int i = 0; i < 16; ++i) S[qg][i] = 0.f;
; #pragma unroll
;         for (int ks = 0; ks < NKS; ++ks) {
;           const h8 kf = *(const h8*)(ksm + (st * 32) * KSTR + ks * 16);
; #pragma unroll
;           for (int qg = 0; qg < NQG; ++qg) S[qg] = __builtin_amdgcn_mfma_f32_32x32x16_f16(kf, qf[qg][ks], S[qg], 0, 0, 0);
;         }
;         if (masked) {
;           const int cb = st * 32;
;           const int dr = krow - rq + 7;
; #pragma unroll
;           for (int qg = 0; qg < NQG; ++qg) {
;             const int qc = qg * 32 + r;
;             const int cs = min(max(qc - 8, 0), 48);
; #pragma unroll
;             for (int i = 0; i < 16; ++i) {
;               const int c = cb + (i & 3) + 8 * (i >> 2) + 4 * h;
;               const bool valid = (c >= cs) && (c < cs + 16);
;               float bias = 0.f;
;               if (valid) bias = rpb_h[dr * 31 + (c - qc + 15)] * LOG2E;
;               S[qg][i] = valid ? S[qg][i] + bias : -1e30f;
;             }
;           }
;         }
;         h4 vf[2][2][2];
; #pragma unroll
;         for (int dvt = 0; dvt < 2; ++dvt)
; #pragma unroll
;           for (int sx = 0; sx < 2; ++sx)
; #pragma unroll
;             for (int hf = 0; hf < 2; ++hf) vf[dvt][sx][hf] = *(const h4*)(vsm + (dvt * 32) * VSTR + st * 32 + sx * 16 + hf * 8);
; #pragma unroll
;         for (int qg = 0; qg < NQG; ++qg) {
;           h8 P[2];
;           float mx = S[qg][0];
; #pragma unroll
;           for (int i = 1; i < 16; ++i) mx = fmaxf(mx, S[qg][i]);
;           mx = fmaxf(mx, __shfl_xor(mx, 32));
;           if (__builtin_amdgcn_ballot_w64(mx > mrun[qg] + 8.f) != 0ull) {
;             const float mnew = fmaxf(mrun[qg], mx);
;             const float alpha = __builtin_amdgcn_exp2f(mrun[qg] - mnew);
;             lrun[qg] *= alpha;
; #pragma unroll
;             for (int dvt = 0; dvt < 2; ++dvt)
; #pragma unroll
;               for (int i = 0; i < 16; ++i) O[dvt][qg][i] *= alpha;
;             mrun[qg] = mnew;
.Lnoinit_diff1c:
	ds_read_b128 v[2:5], v15 offset:0
	ds_read_b128 v[6:9], v15 offset:32
	ds_read2_b64 v[10:13], v183 offset0:0 offset1:2
	ds_read2_b64 v[136:139], v183 offset0:4 offset1:6
	ds_read2_b64 v[150:153], v187 offset0:0 offset1:2
	ds_read2_b64 v[190:193], v187 offset0:4 offset1:6
	s_waitcnt lgkmcnt(5)
	v_mfma_f32_32x32x16_f16 v[96:111], v[2:5], v[112:115], v[196:211]
	s_waitcnt lgkmcnt(4)
	v_mfma_f32_32x32x16_f16 v[96:111], v[6:9], v[116:119], v[96:111]
	s_cmp_lg_u32 s19, 0
	s_cbranch_scc1 .Lfirst_diff1c_0
.Lcontf_diff1c_0:
	s_nop 9
	v_exp_f32_e32 v96, v96
	v_exp_f32_e32 v97, v97
	v_exp_f32_e32 v98, v98
	v_exp_f32_e32 v99, v99
	v_exp_f32_e32 v100, v100
	v_exp_f32_e32 v101, v101
	v_mfma_f32_32x32x16_f16 v[80:95], v[2:5], v[120:123], v[212:227]
	v_exp_f32_e32 v102, v102
	v_exp_f32_e32 v103, v103
	v_exp_f32_e32 v104, v104
	v_exp_f32_e32 v105, v105
	v_exp_f32_e32 v106, v106
	v_exp_f32_e32 v107, v107
	v_exp_f32_e32 v108, v108
	v_exp_f32_e32 v109, v109
	v_exp_f32_e32 v110, v110
	v_exp_f32_e32 v111, v111
	v_mfma_f32_32x32x16_f16 v[80:95], v[6:9], v[124:127], v[80:95]
	v_cvt_pk_f16_f32 v228, v96, v97
	v_cvt_pk_f16_f32 v229, v98, v99
	v_cvt_pk_f16_f32 v230, v100, v101
	v_cvt_pk_f16_f32 v231, v102, v103
	v_cvt_pk_f16_f32 v232, v104, v105
	v_cvt_pk_f16_f32 v233, v106, v107
	v_cvt_pk_f16_f32 v234, v108, v109
	v_cvt_pk_f16_f32 v235, v110, v111
	v_pk_add_f32 v[96:97], v[96:97], v[98:99]
	v_pk_add_f32 v[100:101], v[100:101], v[102:103]
	v_pk_add_f32 v[104:105], v[104:105], v[106:107]
	v_pk_add_f32 v[108:109], v[108:109], v[110:111]
	v_pk_add_f32 v[96:97], v[96:97], v[100:101]
	v_pk_add_f32 v[104:105], v[104:105], v[108:109]
	v_pk_add_f32 v[96:97], v[96:97], v[104:105]
	v_add_f32_e32 v96, v96, v97
	v_cmp_lt_f32_e32 vcc, 0x43800000, v96
	s_cbranch_vccnz .Leager_diff1c_0
.Lcont_diff1c_0:
	v_add_f32_e32 v149, v149, v96
	ds_read_b128 v[2:5], v15 offset:2560
	ds_read_b128 v[6:9], v15 offset:2592
	s_cmp_lg_u32 s19, 0
	s_cbranch_scc1 .Lfirst_diff1c_1
.Lcontf_diff1c_1:
	v_exp_f32_e32 v80, v80
	s_waitcnt lgkmcnt(5)
	v_mfma_f32_32x32x16_f16 v[64:79], v[10:13], v[228:231], v[64:79]
	v_exp_f32_e32 v81, v81
	v_exp_f32_e32 v82, v82
	v_exp_f32_e32 v83, v83
	v_exp_f32_e32 v84, v84
	s_waitcnt lgkmcnt(3)
	v_mfma_f32_32x32x16_f16 v[32:47], v[150:153], v[228:231], v[32:47]
	v_exp_f32_e32 v85, v85
	v_exp_f32_e32 v86, v86
	v_exp_f32_e32 v87, v87
	v_exp_f32_e32 v88, v88
	v_mfma_f32_32x32x16_f16 v[64:79], v[136:139], v[232:235], v[64:79]
	v_exp_f32_e32 v89, v89
	v_exp_f32_e32 v90, v90
	v_exp_f32_e32 v91, v91
	v_exp_f32_e32 v92, v92
	s_waitcnt lgkmcnt(2)
	v_mfma_f32_32x32x16_f16 v[32:47], v[190:193], v[232:235], v[32:47]
	v_exp_f32_e32 v93, v93
	v_exp_f32_e32 v94, v94
	v_exp_f32_e32 v95, v95
	s_waitcnt lgkmcnt(1)
	v_mfma_f32_32x32x16_f16 v[96:111], v[2:5], v[112:115], v[196:211]
	v_cvt_pk_f16_f32 v228, v80, v81
	v_cvt_pk_f16_f32 v229, v82, v83
	v_cvt_pk_f16_f32 v230, v84, v85
	v_cvt_pk_f16_f32 v231, v86, v87
	s_waitcnt lgkmcnt(0)
	v_mfma_f32_32x32x16_f16 v[96:111], v[6:9], v[116:119], v[96:111]
	v_cvt_pk_f16_f32 v232, v88, v89
	v_cvt_pk_f16_f32 v233, v90, v91
	v_cvt_pk_f16_f32 v234, v92, v93
	v_cvt_pk_f16_f32 v235, v94, v95
	v_pk_add_f32 v[80:81], v[80:81], v[82:83]
	v_pk_add_f32 v[84:85], v[84:85], v[86:87]
	v_pk_add_f32 v[88:89], v[88:89], v[90:91]
	v_pk_add_f32 v[92:93], v[92:93], v[94:95]
	v_pk_add_f32 v[80:81], v[80:81], v[84:85]
	v_pk_add_f32 v[88:89], v[88:89], v[92:93]
	v_pk_add_f32 v[80:81], v[80:81], v[88:89]
	v_add_f32_e32 v80, v80, v81
	v_cmp_lt_f32_e32 vcc, 0x43800000, v80
	s_cbranch_vccnz .Leager_diff1c_1
.Lcont_diff1c_1:
	v_add_f32_e32 v1, v1, v80
	v_exp_f32_e32 v96, v96
	v_exp_f32_e32 v97, v97
	v_mfma_f32_32x32x16_f16 v[48:63], v[10:13], v[228:231], v[48:63]
	v_exp_f32_e32 v98, v98
	v_exp_f32_e32 v99, v99
	v_exp_f32_e32 v100, v100
	v_exp_f32_e32 v101, v101
	v_mfma_f32_32x32x16_f16 v[16:31], v[150:153], v[228:231], v[16:31]
	v_exp_f32_e32 v102, v102
	v_exp_f32_e32 v103, v103
	v_exp_f32_e32 v104, v104
	v_mfma_f32_32x32x16_f16 v[48:63], v[136:139], v[232:235], v[48:63]
	v_exp_f32_e32 v105, v105
	v_exp_f32_e32 v106, v106
	v_exp_f32_e32 v107, v107
	v_exp_f32_e32 v108, v108
	v_mfma_f32_32x32x16_f16 v[16:31], v[190:193], v[232:235], v[16:31]
	ds_read2_b64 v[10:13], v183 offset0:8 offset1:10
	ds_read2_b64 v[136:139], v183 offset0:12 offset1:14
	ds_read2_b64 v[150:153], v187 offset0:8 offset1:10
	ds_read2_b64 v[190:193], v187 offset0:12 offset1:14
	v_exp_f32_e32 v109, v109
	v_exp_f32_e32 v110, v110
	v_exp_f32_e32 v111, v111
	v_mfma_f32_32x32x16_f16 v[80:95], v[2:5], v[120:123], v[212:227]
	v_cvt_pk_f16_f32 v228, v96, v97
	v_cvt_pk_f16_f32 v229, v98, v99
	v_cvt_pk_f16_f32 v230, v100, v101
	v_cvt_pk_f16_f32 v231, v102, v103
	v_mfma_f32_32x32x16_f16 v[80:95], v[6:9], v[124:127], v[80:95]
	v_cvt_pk_f16_f32 v232, v104, v105
	v_cvt_pk_f16_f32 v233, v106, v107
	v_cvt_pk_f16_f32 v234, v108, v109
	v_cvt_pk_f16_f32 v235, v110, v111
	v_pk_add_f32 v[96:97], v[96:97], v[98:99]
	v_pk_add_f32 v[100:101], v[100:101], v[102:103]
	v_pk_add_f32 v[104:105], v[104:105], v[106:107]
	v_pk_add_f32 v[108:109], v[108:109], v[110:111]
	v_pk_add_f32 v[96:97], v[96:97], v[100:101]
	v_pk_add_f32 v[104:105], v[104:105], v[108:109]
	v_pk_add_f32 v[96:97], v[96:97], v[104:105]
	v_add_f32_e32 v96, v96, v97
	v_cmp_lt_f32_e32 vcc, 0x43800000, v96
	s_cbranch_vccnz .Leager_diff1c_2
; template <int DQ, bool NA, int NQG>
; DI void attn_wg(const half_t* Qp, const half_t* Kp, const half_t* Vp, int q0, bool active, int seg0_start, int seg0_tiles,
;                 int seg1_start, int seg1_tiles, const float* rpb_h, int rq, char* smem, int tid, f16v (&O)[2][NQG]) {
;     ...
;       for (int st = 0; st < 2; ++st) {
;         f16v S[NQG];
; #pragma unroll
;         for (int qg = 0; qg < NQG; ++qg)
; #pragma unroll
;           for (int i = 0; i < 16; ++i) S[qg][i] = 0.f;
; #pragma unroll
;         for (int ks = 0; ks < NKS; ++ks) {
;           const h8 kf = *(const h8*)(ksm + (st * 32) * KSTR + ks * 16);
; #pragma unroll
;           for (int qg = 0; qg < NQG; ++qg) S[qg] = __builtin_amdgcn_mfma_f32_32x32x16_f16(kf, qf[qg][ks], S[qg], 0, 0, 0);
;         }
;         if (masked) {
;           const int cb = st * 32;
;           const int dr = krow - rq + 7;
; #pragma unroll
;           for (int qg = 0; qg < NQG; ++qg) {
;             const int qc = qg * 32 + r;
;             const int cs = min(max(qc - 8, 0), 48);
; #pragma unroll
;             for (int i = 0; i < 16; ++i) {
;               const int c = cb + (i & 3) + 8 * (i >> 2) + 4 * h;
;               const bool valid = (c >= cs) && (c < cs + 16);
;               float bias = 0.f;
;               if (valid) bias = rpb_h[dr * 31 + (c - qc + 15)] * LOG2E;
;               S[qg][i] = valid ? S[qg][i] + bias : -1e30f;
;             }
;           }
;         }
;         h4 vf[2][2][2];
; #pragma unroll
;         for (int dvt = 0; dvt < 2; ++dvt)
; #pragma unroll
;           for (int sx = 0; sx < 2; ++sx)
; #pragma unroll
;             for (int hf = 0; hf < 2; ++hf) vf[dvt][sx][hf] = *(const h4*)(vsm + (dvt * 32) * VSTR + st * 32 + sx * 16 + hf * 8);
; #pragma unroll
;         for (int qg = 0; qg < NQG; ++qg) {
;           h8 P[2];
;           float mx = S[qg][0];
; #pragma unroll
;           for (int i = 1; i < 16; ++i) mx = fmaxf(mx, S[qg][i]);
;           mx = fmaxf(mx, __shfl_xor(mx, 32));
;           if (__builtin_amdgcn_ballot_w64(mx > mrun[qg] + 8.f) != 0ull) {
;             const float mnew = fmaxf(mrun[qg], mx);
;             const float alpha = __builtin_amdgcn_exp2f(mrun[qg] - mnew);
;             lrun[qg] *= alpha;
; #pragma unroll
;             for (int dvt = 0; dvt < 2; ++dvt)
; #pragma unroll
;               for (int i = 0; i < 16; ++i) O[dvt][qg][i] *= alpha;
;             mrun[qg] = mnew;
.Lcont_diff1c_2:
	v_add_f32_e32 v149, v149, v96
	v_exp_f32_e32 v80, v80
	v_exp_f32_e32 v81, v81
	s_waitcnt lgkmcnt(3)
	v_mfma_f32_32x32x16_f16 v[64:79], v[10:13], v[228:231], v[64:79]
	v_exp_f32_e32 v82, v82
	v_exp_f32_e32 v83, v83
	v_exp_f32_e32 v84, v84
	v_exp_f32_e32 v85, v85
	s_waitcnt lgkmcnt(1)
	v_mfma_f32_32x32x16_f16 v[32:47], v[150:153], v[228:231], v[32:47]
	v_exp_f32_e32 v86, v86
	v_exp_f32_e32 v87, v87
	v_exp_f32_e32 v88, v88
	v_mfma_f32_32x32x16_f16 v[64:79], v[136:139], v[232:235], v[64:79]
	v_exp_f32_e32 v89, v89
	v_exp_f32_e32 v90, v90
	v_exp_f32_e32 v91, v91
	v_exp_f32_e32 v92, v92
	s_waitcnt lgkmcnt(0)
	v_mfma_f32_32x32x16_f16 v[32:47], v[190:193], v[232:235], v[32:47]
	v_exp_f32_e32 v93, v93
	v_exp_f32_e32 v94, v94
	v_exp_f32_e32 v95, v95
	v_cvt_pk_f16_f32 v228, v80, v81
	v_cvt_pk_f16_f32 v229, v82, v83
	v_cvt_pk_f16_f32 v230, v84, v85
	v_cvt_pk_f16_f32 v231, v86, v87
	v_cvt_pk_f16_f32 v232, v88, v89
	v_cvt_pk_f16_f32 v233, v90, v91
	v_cvt_pk_f16_f32 v234, v92, v93
	v_cvt_pk_f16_f32 v235, v94, v95
	v_pk_add_f32 v[80:81], v[80:81], v[82:83]
	v_pk_add_f32 v[84:85], v[84:85], v[86:87]
	v_pk_add_f32 v[88:89], v[88:89], v[90:91]
	v_pk_add_f32 v[92:93], v[92:93], v[94:95]
	v_pk_add_f32 v[80:81], v[80:81], v[84:85]
	v_pk_add_f32 v[88:89], v[88:89], v[92:93]
	v_pk_add_f32 v[80:81], v[80:81], v[88:89]
	v_add_f32_e32 v80, v80, v81
	v_cmp_lt_f32_e32 vcc, 0x43800000, v80
	s_cbranch_vccnz .Leager_diff1c_3
.Lcont_diff1c_3:
	v_add_f32_e32 v1, v1, v80
	v_mfma_f32_32x32x16_f16 v[48:63], v[10:13], v[228:231], v[48:63]
	v_mfma_f32_32x32x16_f16 v[16:31], v[150:153], v[228:231], v[16:31]
	v_mfma_f32_32x32x16_f16 v[48:63], v[136:139], v[232:235], v[48:63]
	v_mfma_f32_32x32x16_f16 v[16:31], v[190:193], v[232:235], v[16:31]
	s_branch .Lend_diff1c
.Lfirst_diff1c_0:
	s_nop 15
	v_max3_f32 v189, v96, v97, v98
	v_max3_f32 v194, v99, v100, v101
	v_max3_f32 v189, v189, v102, v103
	v_max3_f32 v189, v189, v106, v107
	v_max3_f32 v189, v189, v110, v111
	v_max3_f32 v194, v194, v104, v105
	v_max3_f32 v194, v194, v108, v109
	v_max_f32_e32 v189, v189, v194
	v_mov_b32_e32 v194, v189
	s_nop 1
	v_permlane32_swap_b32_e32 v194, v189
	v_max_f32_e32 v189, v189, v194
	v_mov_b32_e32 v194, v189
	s_nop 1
	v_pk_add_f32 v[196:197], v[196:197], v[194:195] op_sel_hi:[1,0] neg_lo:[0,1] neg_hi:[0,1]
	v_pk_add_f32 v[198:199], v[198:199], v[194:195] op_sel_hi:[1,0] neg_lo:[0,1] neg_hi:[0,1]
	v_pk_add_f32 v[200:201], v[200:201], v[194:195] op_sel_hi:[1,0] neg_lo:[0,1] neg_hi:[0,1]
	v_pk_add_f32 v[202:203], v[202:203], v[194:195] op_sel_hi:[1,0] neg_lo:[0,1] neg_hi:[0,1]
	v_pk_add_f32 v[204:205], v[204:205], v[194:195] op_sel_hi:[1,0] neg_lo:[0,1] neg_hi:[0,1]
	v_pk_add_f32 v[206:207], v[206:207], v[194:195] op_sel_hi:[1,0] neg_lo:[0,1] neg_hi:[0,1]
	v_pk_add_f32 v[208:209], v[208:209], v[194:195] op_sel_hi:[1,0] neg_lo:[0,1] neg_hi:[0,1]
	v_pk_add_f32 v[210:211], v[210:211], v[194:195] op_sel_hi:[1,0] neg_lo:[0,1] neg_hi:[0,1]
	v_pk_add_f32 v[96:97], v[96:97], v[194:195] op_sel_hi:[1,0] neg_lo:[0,1] neg_hi:[0,1]
	v_pk_add_f32 v[98:99], v[98:99], v[194:195] op_sel_hi:[1,0] neg_lo:[0,1] neg_hi:[0,1]
	v_pk_add_f32 v[100:101], v[100:101], v[194:195] op_sel_hi:[1,0] neg_lo:[0,1] neg_hi:[0,1]
	v_pk_add_f32 v[102:103], v[102:103], v[194:195] op_sel_hi:[1,0] neg_lo:[0,1] neg_hi:[0,1]
	v_pk_add_f32 v[104:105], v[104:105], v[194:195] op_sel_hi:[1,0] neg_lo:[0,1] neg_hi:[0,1]
	v_pk_add_f32 v[106:107], v[106:107], v[194:195] op_sel_hi:[1,0] neg_lo:[0,1] neg_hi:[0,1]
	v_pk_add_f32 v[108:109], v[108:109], v[194:195] op_sel_hi:[1,0] neg_lo:[0,1] neg_hi:[0,1]
	v_pk_add_f32 v[110:111], v[110:111], v[194:195] op_sel_hi:[1,0] neg_lo:[0,1] neg_hi:[0,1]
	s_branch .Lcontf_diff1c_0
.Leager_diff1c_0:
	s_nop 7
	v_mfma_f32_32x32x16_f16 v[96:111], v[2:5], v[112:115], v[196:211]
	v_mfma_f32_32x32x16_f16 v[96:111], v[6:9], v[116:119], v[96:111]
	s_nop 15
	s_nop 15
	v_max3_f32 v189, v96, v97, v98
	v_max3_f32 v194, v99, v100, v101
	v_max3_f32 v189, v189, v102, v103
	v_max3_f32 v189, v189, v106, v107
	v_max3_f32 v189, v189, v110, v111
	v_max3_f32 v194, v194, v104, v105
	v_max3_f32 v194, v194, v108, v109
	v_max_f32_e32 v189, v189, v194
	v_mov_b32_e32 v194, v189
	s_nop 1
	v_permlane32_swap_b32_e32 v194, v189
	v_max_f32_e32 v189, v189, v194
	v_max_f32_e32 v194, 0, v189
	s_nop 1
	v_pk_add_f32 v[196:197], v[196:197], v[194:195] op_sel_hi:[1,0] neg_lo:[0,1] neg_hi:[0,1]
	v_pk_add_f32 v[198:199], v[198:199], v[194:195] op_sel_hi:[1,0] neg_lo:[0,1] neg_hi:[0,1]
	v_pk_add_f32 v[200:201], v[200:201], v[194:195] op_sel_hi:[1,0] neg_lo:[0,1] neg_hi:[0,1]
	v_pk_add_f32 v[202:203], v[202:203], v[194:195] op_sel_hi:[1,0] neg_lo:[0,1] neg_hi:[0,1]
	v_pk_add_f32 v[204:205], v[204:205], v[194:195] op_sel_hi:[1,0] neg_lo:[0,1] neg_hi:[0,1]
	v_pk_add_f32 v[206:207], v[206:207], v[194:195] op_sel_hi:[1,0] neg_lo:[0,1] neg_hi:[0,1]
	v_pk_add_f32 v[208:209], v[208:209], v[194:195] op_sel_hi:[1,0] neg_lo:[0,1] neg_hi:[0,1]
	v_pk_add_f32 v[210:211], v[210:211], v[194:195] op_sel_hi:[1,0] neg_lo:[0,1] neg_hi:[0,1]
	v_pk_add_f32 v[96:97], v[96:97], v[194:195] op_sel_hi:[1,0] neg_lo:[0,1] neg_hi:[0,1]
	v_pk_add_f32 v[98:99], v[98:99], v[194:195] op_sel_hi:[1,0] neg_lo:[0,1] neg_hi:[0,1]
	v_pk_add_f32 v[100:101], v[100:101], v[194:195] op_sel_hi:[1,0] neg_lo:[0,1] neg_hi:[0,1]
	v_pk_add_f32 v[102:103], v[102:103], v[194:195] op_sel_hi:[1,0] neg_lo:[0,1] neg_hi:[0,1]
	v_pk_add_f32 v[104:105], v[104:105], v[194:195] op_sel_hi:[1,0] neg_lo:[0,1] neg_hi:[0,1]
	v_pk_add_f32 v[106:107], v[106:107], v[194:195] op_sel_hi:[1,0] neg_lo:[0,1] neg_hi:[0,1]
	v_pk_add_f32 v[108:109], v[108:109], v[194:195] op_sel_hi:[1,0] neg_lo:[0,1] neg_hi:[0,1]
; template <int DQ, bool NA, int NQG>
; DI void attn_wg(const half_t* Qp, const half_t* Kp, const half_t* Vp, int q0, bool active, int seg0_start, int seg0_tiles,
;                 int seg1_start, int seg1_tiles, const float* rpb_h, int rq, char* smem, int tid, f16v (&O)[2][NQG]) {
;     ...
;       for (int st = 0; st < 2; ++st) {
;         f16v S[NQG];
; #pragma unroll
;         for (int qg = 0; qg < NQG; ++qg)
; #pragma unroll
;           for (int i = 0; i < 16; ++i) S[qg][i] = 0.f;
; #pragma unroll
;         for (int ks = 0; ks < NKS; ++ks) {
;           const h8 kf = *(const h8*)(ksm + (st * 32) * KSTR + ks * 16);
; #pragma unroll
;           for (int qg = 0; qg < NQG; ++qg) S[qg] = __builtin_amdgcn_mfma_f32_32x32x16_f16(kf, qf[qg][ks], S[qg], 0, 0, 0);
;         }
;         if (masked) {
;           const int cb = st * 32;
;           const int dr = krow - rq + 7;
; #pragma unroll
;           for (int qg = 0; qg < NQG; ++qg) {
;             const int qc = qg * 32 + r;
;             const int cs = min(max(qc - 8, 0), 48);
; #pragma unroll
;             for (int i = 0; i < 16; ++i) {
;               const int c = cb + (i & 3) + 8 * (i >> 2) + 4 * h;
;               const bool valid = (c >= cs) && (c < cs + 16);
;               float bias = 0.f;
;               if (valid) bias = rpb_h[dr * 31 + (c - qc + 15)] * LOG2E;
;               S[qg][i] = valid ? S[qg][i] + bias : -1e30f;
;             }
;           }
;         }
;         h4 vf[2][2][2];
; #pragma unroll
;         for (int dvt = 0; dvt < 2; ++dvt)
; #pragma unroll
;           for (int sx = 0; sx < 2; ++sx)
; #pragma unroll
;             for (int hf = 0; hf < 2; ++hf) vf[dvt][sx][hf] = *(const h4*)(vsm + (dvt * 32) * VSTR + st * 32 + sx * 16 + hf * 8);
; #pragma unroll
;         for (int qg = 0; qg < NQG; ++qg) {
;           h8 P[2];
;           float mx = S[qg][0];
; #pragma unroll
;           for (int i = 1; i < 16; ++i) mx = fmaxf(mx, S[qg][i]);
;           mx = fmaxf(mx, __shfl_xor(mx, 32));
;           if (__builtin_amdgcn_ballot_w64(mx > mrun[qg] + 8.f) != 0ull) {
;             const float mnew = fmaxf(mrun[qg], mx);
;             const float alpha = __builtin_amdgcn_exp2f(mrun[qg] - mnew);
;             lrun[qg] *= alpha;
; #pragma unroll
;             for (int dvt = 0; dvt < 2; ++dvt)
; #pragma unroll
;               for (int i = 0; i < 16; ++i) O[dvt][qg][i] *= alpha;
;             mrun[qg] = mnew;
	v_pk_add_f32 v[110:111], v[110:111], v[194:195] op_sel_hi:[1,0] neg_lo:[0,1] neg_hi:[0,1]
	v_exp_f32_e64 v194, -v194
	s_nop 0
	v_mul_f32_e32 v149, v149, v194
	v_pk_mul_f32 v[64:65], v[64:65], v[194:195] op_sel_hi:[1,0]
	v_pk_mul_f32 v[66:67], v[66:67], v[194:195] op_sel_hi:[1,0]
	v_pk_mul_f32 v[68:69], v[68:69], v[194:195] op_sel_hi:[1,0]
	v_pk_mul_f32 v[70:71], v[70:71], v[194:195] op_sel_hi:[1,0]
	v_pk_mul_f32 v[72:73], v[72:73], v[194:195] op_sel_hi:[1,0]
	v_pk_mul_f32 v[74:75], v[74:75], v[194:195] op_sel_hi:[1,0]
	v_pk_mul_f32 v[76:77], v[76:77], v[194:195] op_sel_hi:[1,0]
	v_pk_mul_f32 v[78:79], v[78:79], v[194:195] op_sel_hi:[1,0]
	v_pk_mul_f32 v[32:33], v[32:33], v[194:195] op_sel_hi:[1,0]
	v_pk_mul_f32 v[34:35], v[34:35], v[194:195] op_sel_hi:[1,0]
	v_pk_mul_f32 v[36:37], v[36:37], v[194:195] op_sel_hi:[1,0]
	v_pk_mul_f32 v[38:39], v[38:39], v[194:195] op_sel_hi:[1,0]
	v_pk_mul_f32 v[40:41], v[40:41], v[194:195] op_sel_hi:[1,0]
	v_pk_mul_f32 v[42:43], v[42:43], v[194:195] op_sel_hi:[1,0]
	v_pk_mul_f32 v[44:45], v[44:45], v[194:195] op_sel_hi:[1,0]
	v_pk_mul_f32 v[46:47], v[46:47], v[194:195] op_sel_hi:[1,0]
	v_exp_f32_e32 v96, v96
	v_exp_f32_e32 v97, v97
	v_exp_f32_e32 v98, v98
	v_exp_f32_e32 v99, v99
	v_exp_f32_e32 v100, v100
	v_exp_f32_e32 v101, v101
	v_exp_f32_e32 v102, v102
	v_exp_f32_e32 v103, v103
	v_exp_f32_e32 v104, v104
	v_exp_f32_e32 v105, v105
	v_exp_f32_e32 v106, v106
	v_exp_f32_e32 v107, v107
	v_exp_f32_e32 v108, v108
	v_exp_f32_e32 v109, v109
	v_exp_f32_e32 v110, v110
	v_exp_f32_e32 v111, v111
	s_nop 0
	v_cvt_pk_f16_f32 v228, v96, v97
	v_cvt_pk_f16_f32 v229, v98, v99
	v_cvt_pk_f16_f32 v230, v100, v101
	v_cvt_pk_f16_f32 v231, v102, v103
	v_cvt_pk_f16_f32 v232, v104, v105
	v_cvt_pk_f16_f32 v233, v106, v107
	v_cvt_pk_f16_f32 v234, v108, v109
	v_cvt_pk_f16_f32 v235, v110, v111
	v_pk_add_f32 v[96:97], v[96:97], v[98:99]
	v_pk_add_f32 v[100:101], v[100:101], v[102:103]
	v_pk_add_f32 v[104:105], v[104:105], v[106:107]
	v_pk_add_f32 v[108:109], v[108:109], v[110:111]
	v_pk_add_f32 v[96:97], v[96:97], v[100:101]
	v_pk_add_f32 v[104:105], v[104:105], v[108:109]
	v_pk_add_f32 v[96:97], v[96:97], v[104:105]
	v_add_f32_e32 v96, v96, v97
	s_branch .Lcont_diff1c_0
.Lfirst_diff1c_1:
	s_nop 15
	v_max3_f32 v189, v80, v81, v82
	v_max3_f32 v194, v83, v84, v85
	v_max3_f32 v189, v189, v86, v87
	v_max3_f32 v189, v189, v90, v91
	v_max3_f32 v189, v189, v94, v95
	v_max3_f32 v194, v194, v88, v89
	v_max3_f32 v194, v194, v92, v93
	v_max_f32_e32 v189, v189, v194
	v_mov_b32_e32 v194, v189
	s_nop 1
	v_permlane32_swap_b32_e32 v194, v189
	v_max_f32_e32 v189, v189, v194
	v_mov_b32_e32 v194, v189
	s_nop 1
	v_pk_add_f32 v[212:213], v[212:213], v[194:195] op_sel_hi:[1,0] neg_lo:[0,1] neg_hi:[0,1]
	v_pk_add_f32 v[214:215], v[214:215], v[194:195] op_sel_hi:[1,0] neg_lo:[0,1] neg_hi:[0,1]
	v_pk_add_f32 v[216:217], v[216:217], v[194:195] op_sel_hi:[1,0] neg_lo:[0,1] neg_hi:[0,1]
	v_pk_add_f32 v[218:219], v[218:219], v[194:195] op_sel_hi:[1,0] neg_lo:[0,1] neg_hi:[0,1]
	v_pk_add_f32 v[220:221], v[220:221], v[194:195] op_sel_hi:[1,0] neg_lo:[0,1] neg_hi:[0,1]
	v_pk_add_f32 v[222:223], v[222:223], v[194:195] op_sel_hi:[1,0] neg_lo:[0,1] neg_hi:[0,1]
	v_pk_add_f32 v[224:225], v[224:225], v[194:195] op_sel_hi:[1,0] neg_lo:[0,1] neg_hi:[0,1]
	v_pk_add_f32 v[226:227], v[226:227], v[194:195] op_sel_hi:[1,0] neg_lo:[0,1] neg_hi:[0,1]
	v_pk_add_f32 v[80:81], v[80:81], v[194:195] op_sel_hi:[1,0] neg_lo:[0,1] neg_hi:[0,1]
	v_pk_add_f32 v[82:83], v[82:83], v[194:195] op_sel_hi:[1,0] neg_lo:[0,1] neg_hi:[0,1]
	v_pk_add_f32 v[84:85], v[84:85], v[194:195] op_sel_hi:[1,0] neg_lo:[0,1] neg_hi:[0,1]
	v_pk_add_f32 v[86:87], v[86:87], v[194:195] op_sel_hi:[1,0] neg_lo:[0,1] neg_hi:[0,1]
	v_pk_add_f32 v[88:89], v[88:89], v[194:195] op_sel_hi:[1,0] neg_lo:[0,1] neg_hi:[0,1]
	v_pk_add_f32 v[90:91], v[90:91], v[194:195] op_sel_hi:[1,0] neg_lo:[0,1] neg_hi:[0,1]
	v_pk_add_f32 v[92:93], v[92:93], v[194:195] op_sel_hi:[1,0] neg_lo:[0,1] neg_hi:[0,1]
	v_pk_add_f32 v[94:95], v[94:95], v[194:195] op_sel_hi:[1,0] neg_lo:[0,1] neg_hi:[0,1]
	s_branch .Lcontf_diff1c_1
; template <int DQ, bool NA, int NQG>
; DI void attn_wg(const half_t* Qp, const half_t* Kp, const half_t* Vp, int q0, bool active, int seg0_start, int seg0_tiles,
;                 int seg1_start, int seg1_tiles, const float* rpb_h, int rq, char* smem, int tid, f16v (&O)[2][NQG]) {
;     ...
;       for (int st = 0; st < 2; ++st) {
;         f16v S[NQG];
; #pragma unroll
;         for (int qg = 0; qg < NQG; ++qg)
; #pragma unroll
;           for (int i = 0; i < 16; ++i) S[qg][i] = 0.f;
; #pragma unroll
;         for (int ks = 0; ks < NKS; ++ks) {
;           const h8 kf = *(const h8*)(ksm + (st * 32) * KSTR + ks * 16);
; #pragma unroll
;           for (int qg = 0; qg < NQG; ++qg) S[qg] = __builtin_amdgcn_mfma_f32_32x32x16_f16(kf, qf[qg][ks], S[qg], 0, 0, 0);
;         }
;         if (masked) {
;           const int cb = st * 32;
;           const int dr = krow - rq + 7;
; #pragma unroll
;           for (int qg = 0; qg < NQG; ++qg) {
;             const int qc = qg * 32 + r;
;             const int cs = min(max(qc - 8, 0), 48);
; #pragma unroll
;             for (int i = 0; i < 16; ++i) {
;               const int c = cb + (i & 3) + 8 * (i >> 2) + 4 * h;
;               const bool valid = (c >= cs) && (c < cs + 16);
;               float bias = 0.f;
;               if (valid) bias = rpb_h[dr * 31 + (c - qc + 15)] * LOG2E;
;               S[qg][i] = valid ? S[qg][i] + bias : -1e30f;
;             }
;           }
;         }
;         h4 vf[2][2][2];
; #pragma unroll
;         for (int dvt = 0; dvt < 2; ++dvt)
; #pragma unroll
;           for (int sx = 0; sx < 2; ++sx)
; #pragma unroll
;             for (int hf = 0; hf < 2; ++hf) vf[dvt][sx][hf] = *(const h4*)(vsm + (dvt * 32) * VSTR + st * 32 + sx * 16 + hf * 8);
; #pragma unroll
;         for (int qg = 0; qg < NQG; ++qg) {
;           h8 P[2];
;           float mx = S[qg][0];
; #pragma unroll
;           for (int i = 1; i < 16; ++i) mx = fmaxf(mx, S[qg][i]);
;           mx = fmaxf(mx, __shfl_xor(mx, 32));
;           if (__builtin_amdgcn_ballot_w64(mx > mrun[qg] + 8.f) != 0ull) {
;             const float mnew = fmaxf(mrun[qg], mx);
;             const float alpha = __builtin_amdgcn_exp2f(mrun[qg] - mnew);
;             lrun[qg] *= alpha;
; #pragma unroll
;             for (int dvt = 0; dvt < 2; ++dvt)
; #pragma unroll
;               for (int i = 0; i < 16; ++i) O[dvt][qg][i] *= alpha;
;             mrun[qg] = mnew;
.Leager_diff1c_1:
	ds_read_b128 v[2:5], v15 offset:0
	ds_read_b128 v[6:9], v15 offset:32
	s_waitcnt lgkmcnt(0)
	s_nop 7
	v_mfma_f32_32x32x16_f16 v[80:95], v[2:5], v[120:123], v[212:227]
	v_mfma_f32_32x32x16_f16 v[80:95], v[6:9], v[124:127], v[80:95]
	s_nop 15
	s_nop 15
	v_max3_f32 v189, v80, v81, v82
	v_max3_f32 v194, v83, v84, v85
	v_max3_f32 v189, v189, v86, v87
	v_max3_f32 v189, v189, v90, v91
	v_max3_f32 v189, v189, v94, v95
	v_max3_f32 v194, v194, v88, v89
	v_max3_f32 v194, v194, v92, v93
	v_max_f32_e32 v189, v189, v194
	v_mov_b32_e32 v194, v189
	s_nop 1
	v_permlane32_swap_b32_e32 v194, v189
	v_max_f32_e32 v189, v189, v194
	ds_read_b128 v[2:5], v15 offset:2560
	ds_read_b128 v[6:9], v15 offset:2592
	v_max_f32_e32 v194, 0, v189
	s_nop 1
	v_pk_add_f32 v[212:213], v[212:213], v[194:195] op_sel_hi:[1,0] neg_lo:[0,1] neg_hi:[0,1]
	v_pk_add_f32 v[214:215], v[214:215], v[194:195] op_sel_hi:[1,0] neg_lo:[0,1] neg_hi:[0,1]
	v_pk_add_f32 v[216:217], v[216:217], v[194:195] op_sel_hi:[1,0] neg_lo:[0,1] neg_hi:[0,1]
	v_pk_add_f32 v[218:219], v[218:219], v[194:195] op_sel_hi:[1,0] neg_lo:[0,1] neg_hi:[0,1]
	v_pk_add_f32 v[220:221], v[220:221], v[194:195] op_sel_hi:[1,0] neg_lo:[0,1] neg_hi:[0,1]
	v_pk_add_f32 v[222:223], v[222:223], v[194:195] op_sel_hi:[1,0] neg_lo:[0,1] neg_hi:[0,1]
	v_pk_add_f32 v[224:225], v[224:225], v[194:195] op_sel_hi:[1,0] neg_lo:[0,1] neg_hi:[0,1]
	v_pk_add_f32 v[226:227], v[226:227], v[194:195] op_sel_hi:[1,0] neg_lo:[0,1] neg_hi:[0,1]
	v_pk_add_f32 v[80:81], v[80:81], v[194:195] op_sel_hi:[1,0] neg_lo:[0,1] neg_hi:[0,1]
	v_pk_add_f32 v[82:83], v[82:83], v[194:195] op_sel_hi:[1,0] neg_lo:[0,1] neg_hi:[0,1]
	v_pk_add_f32 v[84:85], v[84:85], v[194:195] op_sel_hi:[1,0] neg_lo:[0,1] neg_hi:[0,1]
	v_pk_add_f32 v[86:87], v[86:87], v[194:195] op_sel_hi:[1,0] neg_lo:[0,1] neg_hi:[0,1]
	v_pk_add_f32 v[88:89], v[88:89], v[194:195] op_sel_hi:[1,0] neg_lo:[0,1] neg_hi:[0,1]
	v_pk_add_f32 v[90:91], v[90:91], v[194:195] op_sel_hi:[1,0] neg_lo:[0,1] neg_hi:[0,1]
	v_pk_add_f32 v[92:93], v[92:93], v[194:195] op_sel_hi:[1,0] neg_lo:[0,1] neg_hi:[0,1]
	v_pk_add_f32 v[94:95], v[94:95], v[194:195] op_sel_hi:[1,0] neg_lo:[0,1] neg_hi:[0,1]
	v_exp_f32_e64 v194, -v194
	s_nop 0
	v_mul_f32_e32 v1, v1, v194
	v_pk_mul_f32 v[48:49], v[48:49], v[194:195] op_sel_hi:[1,0]
	v_pk_mul_f32 v[50:51], v[50:51], v[194:195] op_sel_hi:[1,0]
	v_pk_mul_f32 v[52:53], v[52:53], v[194:195] op_sel_hi:[1,0]
	v_pk_mul_f32 v[54:55], v[54:55], v[194:195] op_sel_hi:[1,0]
	v_pk_mul_f32 v[56:57], v[56:57], v[194:195] op_sel_hi:[1,0]
	v_pk_mul_f32 v[58:59], v[58:59], v[194:195] op_sel_hi:[1,0]
	v_pk_mul_f32 v[60:61], v[60:61], v[194:195] op_sel_hi:[1,0]
	v_pk_mul_f32 v[62:63], v[62:63], v[194:195] op_sel_hi:[1,0]
	v_pk_mul_f32 v[16:17], v[16:17], v[194:195] op_sel_hi:[1,0]
	v_pk_mul_f32 v[18:19], v[18:19], v[194:195] op_sel_hi:[1,0]
	v_pk_mul_f32 v[20:21], v[20:21], v[194:195] op_sel_hi:[1,0]
	v_pk_mul_f32 v[22:23], v[22:23], v[194:195] op_sel_hi:[1,0]
	v_pk_mul_f32 v[24:25], v[24:25], v[194:195] op_sel_hi:[1,0]
	v_pk_mul_f32 v[26:27], v[26:27], v[194:195] op_sel_hi:[1,0]
	v_pk_mul_f32 v[28:29], v[28:29], v[194:195] op_sel_hi:[1,0]
	v_pk_mul_f32 v[30:31], v[30:31], v[194:195] op_sel_hi:[1,0]
	v_exp_f32_e32 v80, v80
	v_exp_f32_e32 v81, v81
	v_exp_f32_e32 v82, v82
	v_exp_f32_e32 v83, v83
	v_exp_f32_e32 v84, v84
	v_exp_f32_e32 v85, v85
	v_exp_f32_e32 v86, v86
	v_exp_f32_e32 v87, v87
	v_exp_f32_e32 v88, v88
	v_exp_f32_e32 v89, v89
	v_exp_f32_e32 v90, v90
	v_exp_f32_e32 v91, v91
	v_exp_f32_e32 v92, v92
	v_exp_f32_e32 v93, v93
	v_exp_f32_e32 v94, v94
	v_exp_f32_e32 v95, v95
	s_nop 0
	v_cvt_pk_f16_f32 v228, v80, v81
	v_cvt_pk_f16_f32 v229, v82, v83
	v_cvt_pk_f16_f32 v230, v84, v85
	v_cvt_pk_f16_f32 v231, v86, v87
	v_cvt_pk_f16_f32 v232, v88, v89
	v_cvt_pk_f16_f32 v233, v90, v91
	v_cvt_pk_f16_f32 v234, v92, v93
	v_cvt_pk_f16_f32 v235, v94, v95
	v_pk_add_f32 v[80:81], v[80:81], v[82:83]
	v_pk_add_f32 v[84:85], v[84:85], v[86:87]
	v_pk_add_f32 v[88:89], v[88:89], v[90:91]
	v_pk_add_f32 v[92:93], v[92:93], v[94:95]
	v_pk_add_f32 v[80:81], v[80:81], v[84:85]
	v_pk_add_f32 v[88:89], v[88:89], v[92:93]
	v_pk_add_f32 v[80:81], v[80:81], v[88:89]
	v_add_f32_e32 v80, v80, v81
	s_waitcnt lgkmcnt(0)
	s_branch .Lcont_diff1c_1

; template <int DQ, bool NA, int NQG>
; DI void attn_wg(const half_t* Qp, const half_t* Kp, const half_t* Vp, int q0, bool active, int seg0_start, int seg0_tiles,
;                 int seg1_start, int seg1_tiles, const float* rpb_h, int rq, char* smem, int tid, f16v (&O)[2][NQG]) {
;     ...
;       for (int st = 0; st < 2; ++st) {
;         f16v S[NQG];
; #pragma unroll
;         for (int qg = 0; qg < NQG; ++qg)
; #pragma unroll
;           for (int i = 0; i < 16; ++i) S[qg][i] = 0.f;
; #pragma unroll
;         for (int ks = 0; ks < NKS; ++ks) {
;           const h8 kf = *(const h8*)(ksm + (st * 32) * KSTR + ks * 16);
; #pragma unroll
;           for (int qg = 0; qg < NQG; ++qg) S[qg] = __builtin_amdgcn_mfma_f32_32x32x16_f16(kf, qf[qg][ks], S[qg], 0, 0, 0);
;         }
;         if (masked) {
;           const int cb = st * 32;
;           const int dr = krow - rq + 7;
; #pragma unroll
;           for (int qg = 0; qg < NQG; ++qg) {
;             const int qc = qg * 32 + r;
;             const int cs = min(max(qc - 8, 0), 48);
; #pragma unroll
;             for (int i = 0; i < 16; ++i) {
;               const int c = cb + (i & 3) + 8 * (i >> 2) + 4 * h;
;               const bool valid = (c >= cs) && (c < cs + 16);
;               float bias = 0.f;
;               if (valid) bias = rpb_h[dr * 31 + (c - qc + 15)] * LOG2E;
;               S[qg][i] = valid ? S[qg][i] + bias : -1e30f;
;             }
;           }
;         }
;         h4 vf[2][2][2];
; #pragma unroll
;         for (int dvt = 0; dvt < 2; ++dvt)
; #pragma unroll
;           for (int sx = 0; sx < 2; ++sx)
; #pragma unroll
;             for (int hf = 0; hf < 2; ++hf) vf[dvt][sx][hf] = *(const h4*)(vsm + (dvt * 32) * VSTR + st * 32 + sx * 16 + hf * 8);
; #pragma unroll
;         for (int qg = 0; qg < NQG; ++qg) {
;           h8 P[2];
;           float mx = S[qg][0];
; #pragma unroll
;           for (int i = 1; i < 16; ++i) mx = fmaxf(mx, S[qg][i]);
;           mx = fmaxf(mx, __shfl_xor(mx, 32));
;           if (__builtin_amdgcn_ballot_w64(mx > mrun[qg] + 8.f) != 0ull) {
;             const float mnew = fmaxf(mrun[qg], mx);
;             const float alpha = __builtin_amdgcn_exp2f(mrun[qg] - mnew);
;             lrun[qg] *= alpha;
; #pragma unroll
;             for (int dvt = 0; dvt < 2; ++dvt)
; #pragma unroll
;               for (int i = 0; i < 16; ++i) O[dvt][qg][i] *= alpha;
;             mrun[qg] = mnew;
.Leager_diff1c_3:
	s_nop 7
	v_mfma_f32_32x32x16_f16 v[80:95], v[2:5], v[120:123], v[212:227]
	v_mfma_f32_32x32x16_f16 v[80:95], v[6:9], v[124:127], v[80:95]
	s_nop 15
	s_nop 15
	v_max3_f32 v189, v80, v81, v82
	v_max3_f32 v194, v83, v84, v85
	v_max3_f32 v189, v189, v86, v87
	v_max3_f32 v189, v189, v90, v91
	v_max3_f32 v189, v189, v94, v95
	v_max3_f32 v194, v194, v88, v89
	v_max3_f32 v194, v194, v92, v93
	v_max_f32_e32 v189, v189, v194
	v_mov_b32_e32 v194, v189
	s_nop 1
	v_permlane32_swap_b32_e32 v194, v189
	v_max_f32_e32 v189, v189, v194
	v_max_f32_e32 v194, 0, v189
	s_nop 1
	v_pk_add_f32 v[212:213], v[212:213], v[194:195] op_sel_hi:[1,0] neg_lo:[0,1] neg_hi:[0,1]
	v_pk_add_f32 v[214:215], v[214:215], v[194:195] op_sel_hi:[1,0] neg_lo:[0,1] neg_hi:[0,1]
	v_pk_add_f32 v[216:217], v[216:217], v[194:195] op_sel_hi:[1,0] neg_lo:[0,1] neg_hi:[0,1]
	v_pk_add_f32 v[218:219], v[218:219], v[194:195] op_sel_hi:[1,0] neg_lo:[0,1] neg_hi:[0,1]
	v_pk_add_f32 v[220:221], v[220:221], v[194:195] op_sel_hi:[1,0] neg_lo:[0,1] neg_hi:[0,1]
	v_pk_add_f32 v[222:223], v[222:223], v[194:195] op_sel_hi:[1,0] neg_lo:[0,1] neg_hi:[0,1]
	v_pk_add_f32 v[224:225], v[224:225], v[194:195] op_sel_hi:[1,0] neg_lo:[0,1] neg_hi:[0,1]
	v_pk_add_f32 v[226:227], v[226:227], v[194:195] op_sel_hi:[1,0] neg_lo:[0,1] neg_hi:[0,1]
	v_pk_add_f32 v[80:81], v[80:81], v[194:195] op_sel_hi:[1,0] neg_lo:[0,1] neg_hi:[0,1]
	v_pk_add_f32 v[82:83], v[82:83], v[194:195] op_sel_hi:[1,0] neg_lo:[0,1] neg_hi:[0,1]
	v_pk_add_f32 v[84:85], v[84:85], v[194:195] op_sel_hi:[1,0] neg_lo:[0,1] neg_hi:[0,1]
	v_pk_add_f32 v[86:87], v[86:87], v[194:195] op_sel_hi:[1,0] neg_lo:[0,1] neg_hi:[0,1]
	v_pk_add_f32 v[88:89], v[88:89], v[194:195] op_sel_hi:[1,0] neg_lo:[0,1] neg_hi:[0,1]
	v_pk_add_f32 v[90:91], v[90:91], v[194:195] op_sel_hi:[1,0] neg_lo:[0,1] neg_hi:[0,1]
	v_pk_add_f32 v[92:93], v[92:93], v[194:195] op_sel_hi:[1,0] neg_lo:[0,1] neg_hi:[0,1]
	v_pk_add_f32 v[94:95], v[94:95], v[194:195] op_sel_hi:[1,0] neg_lo:[0,1] neg_hi:[0,1]
	v_exp_f32_e64 v194, -v194
	s_nop 0
	v_mul_f32_e32 v1, v1, v194
	v_pk_mul_f32 v[48:49], v[48:49], v[194:195] op_sel_hi:[1,0]
	v_pk_mul_f32 v[50:51], v[50:51], v[194:195] op_sel_hi:[1,0]
	v_pk_mul_f32 v[52:53], v[52:53], v[194:195] op_sel_hi:[1,0]
	v_pk_mul_f32 v[54:55], v[54:55], v[194:195] op_sel_hi:[1,0]
	v_pk_mul_f32 v[56:57], v[56:57], v[194:195] op_sel_hi:[1,0]
	v_pk_mul_f32 v[58:59], v[58:59], v[194:195] op_sel_hi:[1,0]
	v_pk_mul_f32 v[60:61], v[60:61], v[194:195] op_sel_hi:[1,0]
	v_pk_mul_f32 v[62:63], v[62:63], v[194:195] op_sel_hi:[1,0]
	v_pk_mul_f32 v[16:17], v[16:17], v[194:195] op_sel_hi:[1,0]
	v_pk_mul_f32 v[18:19], v[18:19], v[194:195] op_sel_hi:[1,0]
	v_pk_mul_f32 v[20:21], v[20:21], v[194:195] op_sel_hi:[1,0]
	v_pk_mul_f32 v[22:23], v[22:23], v[194:195] op_sel_hi:[1,0]
	v_pk_mul_f32 v[24:25], v[24:25], v[194:195] op_sel_hi:[1,0]
	v_pk_mul_f32 v[26:27], v[26:27], v[194:195] op_sel_hi:[1,0]
	v_pk_mul_f32 v[28:29], v[28:29], v[194:195] op_sel_hi:[1,0]
	v_pk_mul_f32 v[30:31], v[30:31], v[194:195] op_sel_hi:[1,0]
	v_exp_f32_e32 v80, v80
	v_exp_f32_e32 v81, v81
	v_exp_f32_e32 v82, v82
	v_exp_f32_e32 v83, v83
	v_exp_f32_e32 v84, v84
	v_exp_f32_e32 v85, v85
	v_exp_f32_e32 v86, v86
	v_exp_f32_e32 v87, v87
	v_exp_f32_e32 v88, v88
	v_exp_f32_e32 v89, v89
	v_exp_f32_e32 v90, v90
	v_exp_f32_e32 v91, v91
	v_exp_f32_e32 v92, v92
	v_exp_f32_e32 v93, v93
	v_exp_f32_e32 v94, v94
	v_exp_f32_e32 v95, v95
	s_nop 0
	v_cvt_pk_f16_f32 v228, v80, v81
	v_cvt_pk_f16_f32 v229, v82, v83
	v_cvt_pk_f16_f32 v230, v84, v85
	v_cvt_pk_f16_f32 v231, v86, v87
	v_cvt_pk_f16_f32 v232, v88, v89
	v_cvt_pk_f16_f32 v233, v90, v91
	v_cvt_pk_f16_f32 v234, v92, v93
	v_cvt_pk_f16_f32 v235, v94, v95
	v_pk_add_f32 v[80:81], v[80:81], v[82:83]
	v_pk_add_f32 v[84:85], v[84:85], v[86:87]
	v_pk_add_f32 v[88:89], v[88:89], v[90:91]
	v_pk_add_f32 v[92:93], v[92:93], v[94:95]
	v_pk_add_f32 v[80:81], v[80:81], v[84:85]
	v_pk_add_f32 v[88:89], v[88:89], v[92:93]
	v_pk_add_f32 v[80:81], v[80:81], v[88:89]
	v_add_f32_e32 v80, v80, v81
	s_branch .Lcont_diff1c_3

; template <int DQ, bool NA, int NQG>
; DI void attn_wg(const half_t* Qp, const half_t* Kp, const half_t* Vp, int q0, bool active, int seg0_start, int seg0_tiles,
;                 int seg1_start, int seg1_tiles, const float* rpb_h, int rq, char* smem, int tid, f16v (&O)[2][NQG]) {
;     ...
;       for (int st = 0; st < 2; ++st) {
;         f16v S[NQG];
; #pragma unroll
;         for (int qg = 0; qg < NQG; ++qg)
; #pragma unroll
;           for (int i = 0; i < 16; ++i) S[qg][i] = 0.f;
; #pragma unroll
;         for (int ks = 0; ks < NKS; ++ks) {
;           const h8 kf = *(const h8*)(ksm + (st * 32) * KSTR + ks * 16);
; #pragma unroll
;           for (int qg = 0; qg < NQG; ++qg) S[qg] = __builtin_amdgcn_mfma_f32_32x32x16_f16(kf, qf[qg][ks], S[qg], 0, 0, 0);
;         }
;         if (masked) {
;           const int cb = st * 32;
;           const int dr = krow - rq + 7;
; #pragma unroll
;           for (int qg = 0; qg < NQG; ++qg) {
;             const int qc = qg * 32 + r;
;             const int cs = min(max(qc - 8, 0), 48);
; #pragma unroll
;             for (int i = 0; i < 16; ++i) {
;               const int c = cb + (i & 3) + 8 * (i >> 2) + 4 * h;
;               const bool valid = (c >= cs) && (c < cs + 16);
;               float bias = 0.f;
;               if (valid) bias = rpb_h[dr * 31 + (c - qc + 15)] * LOG2E;
;               S[qg][i] = valid ? S[qg][i] + bias : -1e30f;
;             }
;           }
;         }
;         h4 vf[2][2][2];
; #pragma unroll
;         for (int dvt = 0; dvt < 2; ++dvt)
; #pragma unroll
;           for (int sx = 0; sx < 2; ++sx)
; #pragma unroll
;             for (int hf = 0; hf < 2; ++hf) vf[dvt][sx][hf] = *(const h4*)(vsm + (dvt * 32) * VSTR + st * 32 + sx * 16 + hf * 8);
; #pragma unroll
;         for (int qg = 0; qg < NQG; ++qg) {
;           h8 P[2];
;           float mx = S[qg][0];
; #pragma unroll
;           for (int i = 1; i < 16; ++i) mx = fmaxf(mx, S[qg][i]);
;           mx = fmaxf(mx, __shfl_xor(mx, 32));
;           if (__builtin_amdgcn_ballot_w64(mx > mrun[qg] + 8.f) != 0ull) {
;             const float mnew = fmaxf(mrun[qg], mx);
;             const float alpha = __builtin_amdgcn_exp2f(mrun[qg] - mnew);
;             lrun[qg] *= alpha;
; #pragma unroll
;             for (int dvt = 0; dvt < 2; ++dvt)
; #pragma unroll
;               for (int i = 0; i < 16; ++i) O[dvt][qg][i] *= alpha;
;             mrun[qg] = mnew;
.Lnoinit_diff2c:
	ds_read_b128 v[2:5], v15 offset:0
	ds_read_b128 v[6:9], v15 offset:32
	ds_read2_b64 v[10:13], v151 offset0:0 offset1:2
	ds_read2_b64 v[136:139], v151 offset0:4 offset1:6
	ds_read2_b64 v[146:149], v152 offset0:0 offset1:2
	ds_read2_b64 v[190:193], v152 offset0:4 offset1:6
	s_waitcnt lgkmcnt(5)
	v_mfma_f32_32x32x16_f16 v[96:111], v[2:5], v[112:115], v[196:211]
	s_waitcnt lgkmcnt(4)
	v_mfma_f32_32x32x16_f16 v[96:111], v[6:9], v[116:119], v[96:111]
	s_cmp_lg_u32 s17, 0
	s_cbranch_scc1 .Lfirst_diff2c_0

; template <int DQ, bool NA, int NQG>
; DI void attn_wg(const half_t* Qp, const half_t* Kp, const half_t* Vp, int q0, bool active, int seg0_start, int seg0_tiles,
;                 int seg1_start, int seg1_tiles, const float* rpb_h, int rq, char* smem, int tid, f16v (&O)[2][NQG]) {
;     ...
;       for (int st = 0; st < 2; ++st) {
;         f16v S[NQG];
; #pragma unroll
;         for (int qg = 0; qg < NQG; ++qg)
; #pragma unroll
;           for (int i = 0; i < 16; ++i) S[qg][i] = 0.f;
; #pragma unroll
;         for (int ks = 0; ks < NKS; ++ks) {
;           const h8 kf = *(const h8*)(ksm + (st * 32) * KSTR + ks * 16);
; #pragma unroll
;           for (int qg = 0; qg < NQG; ++qg) S[qg] = __builtin_amdgcn_mfma_f32_32x32x16_f16(kf, qf[qg][ks], S[qg], 0, 0, 0);
;         }
;         if (masked) {
;           const int cb = st * 32;
;           const int dr = krow - rq + 7;
; #pragma unroll
;           for (int qg = 0; qg < NQG; ++qg) {
;             const int qc = qg * 32 + r;
;             const int cs = min(max(qc - 8, 0), 48);
; #pragma unroll
;             for (int i = 0; i < 16; ++i) {
;               const int c = cb + (i & 3) + 8 * (i >> 2) + 4 * h;
;               const bool valid = (c >= cs) && (c < cs + 16);
;               float bias = 0.f;
;               if (valid) bias = rpb_h[dr * 31 + (c - qc + 15)] * LOG2E;
;               S[qg][i] = valid ? S[qg][i] + bias : -1e30f;
;             }
;           }
;         }
;         h4 vf[2][2][2];
; #pragma unroll
;         for (int dvt = 0; dvt < 2; ++dvt)
; #pragma unroll
;           for (int sx = 0; sx < 2; ++sx)
; #pragma unroll
;             for (int hf = 0; hf < 2; ++hf) vf[dvt][sx][hf] = *(const h4*)(vsm + (dvt * 32) * VSTR + st * 32 + sx * 16 + hf * 8);
; #pragma unroll
;         for (int qg = 0; qg < NQG; ++qg) {
;           h8 P[2];
;           float mx = S[qg][0];
; #pragma unroll
;           for (int i = 1; i < 16; ++i) mx = fmaxf(mx, S[qg][i]);
;           mx = fmaxf(mx, __shfl_xor(mx, 32));
;           if (__builtin_amdgcn_ballot_w64(mx > mrun[qg] + 8.f) != 0ull) {
;             const float mnew = fmaxf(mrun[qg], mx);
;             const float alpha = __builtin_amdgcn_exp2f(mrun[qg] - mnew);
;             lrun[qg] *= alpha;
; #pragma unroll
;             for (int dvt = 0; dvt < 2; ++dvt)
; #pragma unroll
;               for (int i = 0; i < 16; ++i) O[dvt][qg][i] *= alpha;
;             mrun[qg] = mnew;
.Lcont_diff2c_0:
	v_add_f32_e32 v145, v145, v96
	ds_read_b128 v[2:5], v15 offset:2560
	ds_read_b128 v[6:9], v15 offset:2592
	s_cmp_lg_u32 s17, 0
	s_cbranch_scc1 .Lfirst_diff2c_1
.Lcontf_diff2c_1:
	v_exp_f32_e32 v80, v80
	s_waitcnt lgkmcnt(5)
	v_mfma_f32_32x32x16_f16 v[64:79], v[10:13], v[228:231], v[64:79]
	v_exp_f32_e32 v81, v81
	v_exp_f32_e32 v82, v82
	v_exp_f32_e32 v83, v83
	v_exp_f32_e32 v84, v84
	s_waitcnt lgkmcnt(3)
	v_mfma_f32_32x32x16_f16 v[48:63], v[146:149], v[228:231], v[48:63]
	v_exp_f32_e32 v85, v85
	v_exp_f32_e32 v86, v86
	v_exp_f32_e32 v87, v87
	v_exp_f32_e32 v88, v88
	v_mfma_f32_32x32x16_f16 v[64:79], v[136:139], v[232:235], v[64:79]
	v_exp_f32_e32 v89, v89
	v_exp_f32_e32 v90, v90
	v_exp_f32_e32 v91, v91
	v_exp_f32_e32 v92, v92
	s_waitcnt lgkmcnt(2)
	v_mfma_f32_32x32x16_f16 v[48:63], v[190:193], v[232:235], v[48:63]
	v_exp_f32_e32 v93, v93
	v_exp_f32_e32 v94, v94
	v_exp_f32_e32 v95, v95
	s_waitcnt lgkmcnt(1)
	v_mfma_f32_32x32x16_f16 v[96:111], v[2:5], v[112:115], v[196:211]
	v_cvt_pk_f16_f32 v228, v80, v81
	v_cvt_pk_f16_f32 v229, v82, v83
	v_cvt_pk_f16_f32 v230, v84, v85
	v_cvt_pk_f16_f32 v231, v86, v87
	s_waitcnt lgkmcnt(0)
	v_mfma_f32_32x32x16_f16 v[96:111], v[6:9], v[116:119], v[96:111]
	v_cvt_pk_f16_f32 v232, v88, v89
	v_cvt_pk_f16_f32 v233, v90, v91
	v_cvt_pk_f16_f32 v234, v92, v93
	v_cvt_pk_f16_f32 v235, v94, v95
	v_pk_add_f32 v[80:81], v[80:81], v[82:83]
	v_pk_add_f32 v[84:85], v[84:85], v[86:87]
	v_pk_add_f32 v[88:89], v[88:89], v[90:91]
	v_pk_add_f32 v[92:93], v[92:93], v[94:95]
	v_pk_add_f32 v[80:81], v[80:81], v[84:85]
	v_pk_add_f32 v[88:89], v[88:89], v[92:93]
	v_pk_add_f32 v[80:81], v[80:81], v[88:89]
	v_add_f32_e32 v80, v80, v81
	v_cmp_lt_f32_e32 vcc, 0x43800000, v80
	s_cbranch_vccnz .Leager_diff2c_1
.Lcont_diff2c_1:
	v_add_f32_e32 v1, v1, v80
	v_exp_f32_e32 v96, v96
	v_exp_f32_e32 v97, v97
	v_mfma_f32_32x32x16_f16 v[32:47], v[10:13], v[228:231], v[32:47]
	v_exp_f32_e32 v98, v98
	v_exp_f32_e32 v99, v99
	v_exp_f32_e32 v100, v100
	v_exp_f32_e32 v101, v101
	v_mfma_f32_32x32x16_f16 v[16:31], v[146:149], v[228:231], v[16:31]
	v_exp_f32_e32 v102, v102
	v_exp_f32_e32 v103, v103
	v_exp_f32_e32 v104, v104
	v_mfma_f32_32x32x16_f16 v[32:47], v[136:139], v[232:235], v[32:47]
	v_exp_f32_e32 v105, v105
	v_exp_f32_e32 v106, v106
	v_exp_f32_e32 v107, v107
	v_exp_f32_e32 v108, v108
	v_mfma_f32_32x32x16_f16 v[16:31], v[190:193], v[232:235], v[16:31]
	ds_read2_b64 v[10:13], v151 offset0:8 offset1:10
	ds_read2_b64 v[136:139], v151 offset0:12 offset1:14
	ds_read2_b64 v[146:149], v152 offset0:8 offset1:10
	ds_read2_b64 v[190:193], v152 offset0:12 offset1:14
	v_exp_f32_e32 v109, v109
	v_exp_f32_e32 v110, v110
	v_exp_f32_e32 v111, v111
	v_mfma_f32_32x32x16_f16 v[80:95], v[2:5], v[120:123], v[212:227]
	v_cvt_pk_f16_f32 v228, v96, v97
	v_cvt_pk_f16_f32 v229, v98, v99
	v_cvt_pk_f16_f32 v230, v100, v101
	v_cvt_pk_f16_f32 v231, v102, v103
	v_mfma_f32_32x32x16_f16 v[80:95], v[6:9], v[124:127], v[80:95]
	v_cvt_pk_f16_f32 v232, v104, v105
	v_cvt_pk_f16_f32 v233, v106, v107
	v_cvt_pk_f16_f32 v234, v108, v109
	v_cvt_pk_f16_f32 v235, v110, v111
	v_pk_add_f32 v[96:97], v[96:97], v[98:99]
	v_pk_add_f32 v[100:101], v[100:101], v[102:103]
	v_pk_add_f32 v[104:105], v[104:105], v[106:107]
	v_pk_add_f32 v[108:109], v[108:109], v[110:111]
	v_pk_add_f32 v[96:97], v[96:97], v[100:101]
	v_pk_add_f32 v[104:105], v[104:105], v[108:109]
	v_pk_add_f32 v[96:97], v[96:97], v[104:105]
	v_add_f32_e32 v96, v96, v97
	v_cmp_lt_f32_e32 vcc, 0x43800000, v96
	s_cbranch_vccnz .Leager_diff2c_2
.Lcont_diff2c_2:
	v_add_f32_e32 v145, v145, v96
	v_exp_f32_e32 v80, v80
	v_exp_f32_e32 v81, v81
	s_waitcnt lgkmcnt(3)
	v_mfma_f32_32x32x16_f16 v[64:79], v[10:13], v[228:231], v[64:79]
	v_exp_f32_e32 v82, v82
	v_exp_f32_e32 v83, v83
	v_exp_f32_e32 v84, v84
	v_exp_f32_e32 v85, v85
	s_waitcnt lgkmcnt(1)
	v_mfma_f32_32x32x16_f16 v[48:63], v[146:149], v[228:231], v[48:63]
	v_exp_f32_e32 v86, v86
	v_exp_f32_e32 v87, v87
	v_exp_f32_e32 v88, v88
	v_mfma_f32_32x32x16_f16 v[64:79], v[136:139], v[232:235], v[64:79]
	v_exp_f32_e32 v89, v89
	v_exp_f32_e32 v90, v90
	v_exp_f32_e32 v91, v91
	v_exp_f32_e32 v92, v92
	s_waitcnt lgkmcnt(0)
	v_mfma_f32_32x32x16_f16 v[48:63], v[190:193], v[232:235], v[48:63]
	v_exp_f32_e32 v93, v93
	v_exp_f32_e32 v94, v94
	v_exp_f32_e32 v95, v95
	v_cvt_pk_f16_f32 v228, v80, v81
	v_cvt_pk_f16_f32 v229, v82, v83
	v_cvt_pk_f16_f32 v230, v84, v85
	v_cvt_pk_f16_f32 v231, v86, v87
	v_cvt_pk_f16_f32 v232, v88, v89
	v_cvt_pk_f16_f32 v233, v90, v91
	v_cvt_pk_f16_f32 v234, v92, v93
	v_cvt_pk_f16_f32 v235, v94, v95
	v_pk_add_f32 v[80:81], v[80:81], v[82:83]
	v_pk_add_f32 v[84:85], v[84:85], v[86:87]
	v_pk_add_f32 v[88:89], v[88:89], v[90:91]
	v_pk_add_f32 v[92:93], v[92:93], v[94:95]
	v_pk_add_f32 v[80:81], v[80:81], v[84:85]
	v_pk_add_f32 v[88:89], v[88:89], v[92:93]
	v_pk_add_f32 v[80:81], v[80:81], v[88:89]
	v_add_f32_e32 v80, v80, v81
	v_cmp_lt_f32_e32 vcc, 0x43800000, v80
	s_cbranch_vccnz .Leager_diff2c_3
.Lcont_diff2c_3:
	v_add_f32_e32 v1, v1, v80
	v_mfma_f32_32x32x16_f16 v[32:47], v[10:13], v[228:231], v[32:47]
	v_mfma_f32_32x32x16_f16 v[16:31], v[146:149], v[228:231], v[16:31]
	v_mfma_f32_32x32x16_f16 v[32:47], v[136:139], v[232:235], v[32:47]
	v_mfma_f32_32x32x16_f16 v[16:31], v[190:193], v[232:235], v[16:31]
	s_branch .Lend_diff2c

; template <int DQ, bool NA, int NQG>
; DI void attn_wg(const half_t* Qp, const half_t* Kp, const half_t* Vp, int q0, bool active, int seg0_start, int seg0_tiles,
;                 int seg1_start, int seg1_tiles, const float* rpb_h, int rq, char* smem, int tid, f16v (&O)[2][NQG]) {
;     ...
;       for (int st = 0; st < 2; ++st) {
;         f16v S[NQG];
; #pragma unroll
;         for (int qg = 0; qg < NQG; ++qg)
; #pragma unroll
;           for (int i = 0; i < 16; ++i) S[qg][i] = 0.f;
; #pragma unroll
;         for (int ks = 0; ks < NKS; ++ks) {
;           const h8 kf = *(const h8*)(ksm + (st * 32) * KSTR + ks * 16);
; #pragma unroll
;           for (int qg = 0; qg < NQG; ++qg) S[qg] = __builtin_amdgcn_mfma_f32_32x32x16_f16(kf, qf[qg][ks], S[qg], 0, 0, 0);
;         }
;         if (masked) {
;           const int cb = st * 32;
;           const int dr = krow - rq + 7;
; #pragma unroll
;           for (int qg = 0; qg < NQG; ++qg) {
;             const int qc = qg * 32 + r;
;             const int cs = min(max(qc - 8, 0), 48);
; #pragma unroll
;             for (int i = 0; i < 16; ++i) {
;               const int c = cb + (i & 3) + 8 * (i >> 2) + 4 * h;
;               const bool valid = (c >= cs) && (c < cs + 16);
;               float bias = 0.f;
;               if (valid) bias = rpb_h[dr * 31 + (c - qc + 15)] * LOG2E;
;               S[qg][i] = valid ? S[qg][i] + bias : -1e30f;
;             }
;           }
;         }
;         h4 vf[2][2][2];
; #pragma unroll
;         for (int dvt = 0; dvt < 2; ++dvt)
; #pragma unroll
;           for (int sx = 0; sx < 2; ++sx)
; #pragma unroll
;             for (int hf = 0; hf < 2; ++hf) vf[dvt][sx][hf] = *(const h4*)(vsm + (dvt * 32) * VSTR + st * 32 + sx * 16 + hf * 8);
; #pragma unroll
;         for (int qg = 0; qg < NQG; ++qg) {
;           h8 P[2];
;           float mx = S[qg][0];
; #pragma unroll
;           for (int i = 1; i < 16; ++i) mx = fmaxf(mx, S[qg][i]);
;           mx = fmaxf(mx, __shfl_xor(mx, 32));
;           if (__builtin_amdgcn_ballot_w64(mx > mrun[qg] + 8.f) != 0ull) {
;             const float mnew = fmaxf(mrun[qg], mx);
;             const float alpha = __builtin_amdgcn_exp2f(mrun[qg] - mnew);
;             lrun[qg] *= alpha;
; #pragma unroll
;             for (int dvt = 0; dvt < 2; ++dvt)
; #pragma unroll
;               for (int i = 0; i < 16; ++i) O[dvt][qg][i] *= alpha;
;             mrun[qg] = mnew;
.Leager_diff2c_0:
	s_nop 7
	v_mfma_f32_32x32x16_f16 v[96:111], v[2:5], v[112:115], v[196:211]
	v_mfma_f32_32x32x16_f16 v[96:111], v[6:9], v[116:119], v[96:111]
	s_nop 15
	s_nop 15
	v_max3_f32 v189, v96, v97, v98
	v_max3_f32 v194, v99, v100, v101
	v_max3_f32 v189, v189, v102, v103
	v_max3_f32 v189, v189, v106, v107
	v_max3_f32 v189, v189, v110, v111
	v_max3_f32 v194, v194, v104, v105
	v_max3_f32 v194, v194, v108, v109
	v_max_f32_e32 v189, v189, v194
	v_mov_b32_e32 v194, v189
	s_nop 1
	v_permlane32_swap_b32_e32 v194, v189
	v_max_f32_e32 v189, v189, v194
	v_max_f32_e32 v194, 0, v189
	s_nop 1
	v_pk_add_f32 v[196:197], v[196:197], v[194:195] op_sel_hi:[1,0] neg_lo:[0,1] neg_hi:[0,1]
	v_pk_add_f32 v[198:199], v[198:199], v[194:195] op_sel_hi:[1,0] neg_lo:[0,1] neg_hi:[0,1]
	v_pk_add_f32 v[200:201], v[200:201], v[194:195] op_sel_hi:[1,0] neg_lo:[0,1] neg_hi:[0,1]
	v_pk_add_f32 v[202:203], v[202:203], v[194:195] op_sel_hi:[1,0] neg_lo:[0,1] neg_hi:[0,1]
	v_pk_add_f32 v[204:205], v[204:205], v[194:195] op_sel_hi:[1,0] neg_lo:[0,1] neg_hi:[0,1]
	v_pk_add_f32 v[206:207], v[206:207], v[194:195] op_sel_hi:[1,0] neg_lo:[0,1] neg_hi:[0,1]
	v_pk_add_f32 v[208:209], v[208:209], v[194:195] op_sel_hi:[1,0] neg_lo:[0,1] neg_hi:[0,1]
	v_pk_add_f32 v[210:211], v[210:211], v[194:195] op_sel_hi:[1,0] neg_lo:[0,1] neg_hi:[0,1]
	v_pk_add_f32 v[96:97], v[96:97], v[194:195] op_sel_hi:[1,0] neg_lo:[0,1] neg_hi:[0,1]
	v_pk_add_f32 v[98:99], v[98:99], v[194:195] op_sel_hi:[1,0] neg_lo:[0,1] neg_hi:[0,1]
	v_pk_add_f32 v[100:101], v[100:101], v[194:195] op_sel_hi:[1,0] neg_lo:[0,1] neg_hi:[0,1]
	v_pk_add_f32 v[102:103], v[102:103], v[194:195] op_sel_hi:[1,0] neg_lo:[0,1] neg_hi:[0,1]
	v_pk_add_f32 v[104:105], v[104:105], v[194:195] op_sel_hi:[1,0] neg_lo:[0,1] neg_hi:[0,1]
	v_pk_add_f32 v[106:107], v[106:107], v[194:195] op_sel_hi:[1,0] neg_lo:[0,1] neg_hi:[0,1]
	v_pk_add_f32 v[108:109], v[108:109], v[194:195] op_sel_hi:[1,0] neg_lo:[0,1] neg_hi:[0,1]
	v_pk_add_f32 v[110:111], v[110:111], v[194:195] op_sel_hi:[1,0] neg_lo:[0,1] neg_hi:[0,1]
	v_exp_f32_e64 v194, -v194
	s_nop 0
	v_mul_f32_e32 v145, v145, v194
	v_pk_mul_f32 v[64:65], v[64:65], v[194:195] op_sel_hi:[1,0]
	v_pk_mul_f32 v[66:67], v[66:67], v[194:195] op_sel_hi:[1,0]
	v_pk_mul_f32 v[68:69], v[68:69], v[194:195] op_sel_hi:[1,0]
	v_pk_mul_f32 v[70:71], v[70:71], v[194:195] op_sel_hi:[1,0]
	v_pk_mul_f32 v[72:73], v[72:73], v[194:195] op_sel_hi:[1,0]
	v_pk_mul_f32 v[74:75], v[74:75], v[194:195] op_sel_hi:[1,0]
	v_pk_mul_f32 v[76:77], v[76:77], v[194:195] op_sel_hi:[1,0]
	v_pk_mul_f32 v[78:79], v[78:79], v[194:195] op_sel_hi:[1,0]
	v_pk_mul_f32 v[48:49], v[48:49], v[194:195] op_sel_hi:[1,0]
	v_pk_mul_f32 v[50:51], v[50:51], v[194:195] op_sel_hi:[1,0]
	v_pk_mul_f32 v[52:53], v[52:53], v[194:195] op_sel_hi:[1,0]
	v_pk_mul_f32 v[54:55], v[54:55], v[194:195] op_sel_hi:[1,0]
	v_pk_mul_f32 v[56:57], v[56:57], v[194:195] op_sel_hi:[1,0]
	v_pk_mul_f32 v[58:59], v[58:59], v[194:195] op_sel_hi:[1,0]
	v_pk_mul_f32 v[60:61], v[60:61], v[194:195] op_sel_hi:[1,0]
	v_pk_mul_f32 v[62:63], v[62:63], v[194:195] op_sel_hi:[1,0]
	v_exp_f32_e32 v96, v96
	v_exp_f32_e32 v97, v97
	v_exp_f32_e32 v98, v98
	v_exp_f32_e32 v99, v99
	v_exp_f32_e32 v100, v100
	v_exp_f32_e32 v101, v101
	v_exp_f32_e32 v102, v102
	v_exp_f32_e32 v103, v103
	v_exp_f32_e32 v104, v104
	v_exp_f32_e32 v105, v105
	v_exp_f32_e32 v106, v106
	v_exp_f32_e32 v107, v107
	v_exp_f32_e32 v108, v108
	v_exp_f32_e32 v109, v109
	v_exp_f32_e32 v110, v110
	v_exp_f32_e32 v111, v111
	s_nop 0
	v_cvt_pk_f16_f32 v228, v96, v97
	v_cvt_pk_f16_f32 v229, v98, v99
	v_cvt_pk_f16_f32 v230, v100, v101
	v_cvt_pk_f16_f32 v231, v102, v103
	v_cvt_pk_f16_f32 v232, v104, v105
	v_cvt_pk_f16_f32 v233, v106, v107
	v_cvt_pk_f16_f32 v234, v108, v109
	v_cvt_pk_f16_f32 v235, v110, v111
	v_pk_add_f32 v[96:97], v[96:97], v[98:99]
	v_pk_add_f32 v[100:101], v[100:101], v[102:103]
	v_pk_add_f32 v[104:105], v[104:105], v[106:107]
	v_pk_add_f32 v[108:109], v[108:109], v[110:111]
	v_pk_add_f32 v[96:97], v[96:97], v[100:101]
	v_pk_add_f32 v[104:105], v[104:105], v[108:109]
	v_pk_add_f32 v[96:97], v[96:97], v[104:105]
	v_add_f32_e32 v96, v96, v97
	s_branch .Lcont_diff2c_0

; template <int DQ, bool NA, int NQG>
; DI void attn_wg(const half_t* Qp, const half_t* Kp, const half_t* Vp, int q0, bool active, int seg0_start, int seg0_tiles,
;                 int seg1_start, int seg1_tiles, const float* rpb_h, int rq, char* smem, int tid, f16v (&O)[2][NQG]) {
;     ...
;       for (int st = 0; st < 2; ++st) {
;         f16v S[NQG];
; #pragma unroll
;         for (int qg = 0; qg < NQG; ++qg)
; #pragma unroll
;           for (int i = 0; i < 16; ++i) S[qg][i] = 0.f;
; #pragma unroll
;         for (int ks = 0; ks < NKS; ++ks) {
;           const h8 kf = *(const h8*)(ksm + (st * 32) * KSTR + ks * 16);
; #pragma unroll
;           for (int qg = 0; qg < NQG; ++qg) S[qg] = __builtin_amdgcn_mfma_f32_32x32x16_f16(kf, qf[qg][ks], S[qg], 0, 0, 0);
;         }
;         if (masked) {
;           const int cb = st * 32;
;           const int dr = krow - rq + 7;
; #pragma unroll
;           for (int qg = 0; qg < NQG; ++qg) {
;             const int qc = qg * 32 + r;
;             const int cs = min(max(qc - 8, 0), 48);
; #pragma unroll
;             for (int i = 0; i < 16; ++i) {
;               const int c = cb + (i & 3) + 8 * (i >> 2) + 4 * h;
;               const bool valid = (c >= cs) && (c < cs + 16);
;               float bias = 0.f;
;               if (valid) bias = rpb_h[dr * 31 + (c - qc + 15)] * LOG2E;
;               S[qg][i] = valid ? S[qg][i] + bias : -1e30f;
;             }
;           }
;         }
;         h4 vf[2][2][2];
; #pragma unroll
;         for (int dvt = 0; dvt < 2; ++dvt)
; #pragma unroll
;           for (int sx = 0; sx < 2; ++sx)
; #pragma unroll
;             for (int hf = 0; hf < 2; ++hf) vf[dvt][sx][hf] = *(const h4*)(vsm + (dvt * 32) * VSTR + st * 32 + sx * 16 + hf * 8);
; #pragma unroll
;         for (int qg = 0; qg < NQG; ++qg) {
;           h8 P[2];
;           float mx = S[qg][0];
; #pragma unroll
;           for (int i = 1; i < 16; ++i) mx = fmaxf(mx, S[qg][i]);
;           mx = fmaxf(mx, __shfl_xor(mx, 32));
;           if (__builtin_amdgcn_ballot_w64(mx > mrun[qg] + 8.f) != 0ull) {
;             const float mnew = fmaxf(mrun[qg], mx);
;             const float alpha = __builtin_amdgcn_exp2f(mrun[qg] - mnew);
;             lrun[qg] *= alpha;
; #pragma unroll
;             for (int dvt = 0; dvt < 2; ++dvt)
; #pragma unroll
;               for (int i = 0; i < 16; ++i) O[dvt][qg][i] *= alpha;
;             mrun[qg] = mnew;
.Leager_diff2c_1:
	ds_read_b128 v[2:5], v15 offset:0
	ds_read_b128 v[6:9], v15 offset:32
	s_waitcnt lgkmcnt(0)
	s_nop 7
	v_mfma_f32_32x32x16_f16 v[80:95], v[2:5], v[120:123], v[212:227]
	v_mfma_f32_32x32x16_f16 v[80:95], v[6:9], v[124:127], v[80:95]
	s_nop 15
	s_nop 15
	v_max3_f32 v189, v80, v81, v82
	v_max3_f32 v194, v83, v84, v85
	v_max3_f32 v189, v189, v86, v87
	v_max3_f32 v189, v189, v90, v91
	v_max3_f32 v189, v189, v94, v95
	v_max3_f32 v194, v194, v88, v89
	v_max3_f32 v194, v194, v92, v93
	v_max_f32_e32 v189, v189, v194
	v_mov_b32_e32 v194, v189
	s_nop 1
	v_permlane32_swap_b32_e32 v194, v189
	v_max_f32_e32 v189, v189, v194
	ds_read_b128 v[2:5], v15 offset:2560
	ds_read_b128 v[6:9], v15 offset:2592
	v_max_f32_e32 v194, 0, v189
	s_nop 1
	v_pk_add_f32 v[212:213], v[212:213], v[194:195] op_sel_hi:[1,0] neg_lo:[0,1] neg_hi:[0,1]
	v_pk_add_f32 v[214:215], v[214:215], v[194:195] op_sel_hi:[1,0] neg_lo:[0,1] neg_hi:[0,1]
	v_pk_add_f32 v[216:217], v[216:217], v[194:195] op_sel_hi:[1,0] neg_lo:[0,1] neg_hi:[0,1]
	v_pk_add_f32 v[218:219], v[218:219], v[194:195] op_sel_hi:[1,0] neg_lo:[0,1] neg_hi:[0,1]
	v_pk_add_f32 v[220:221], v[220:221], v[194:195] op_sel_hi:[1,0] neg_lo:[0,1] neg_hi:[0,1]
	v_pk_add_f32 v[222:223], v[222:223], v[194:195] op_sel_hi:[1,0] neg_lo:[0,1] neg_hi:[0,1]
	v_pk_add_f32 v[224:225], v[224:225], v[194:195] op_sel_hi:[1,0] neg_lo:[0,1] neg_hi:[0,1]
	v_pk_add_f32 v[226:227], v[226:227], v[194:195] op_sel_hi:[1,0] neg_lo:[0,1] neg_hi:[0,1]
	v_pk_add_f32 v[80:81], v[80:81], v[194:195] op_sel_hi:[1,0] neg_lo:[0,1] neg_hi:[0,1]
	v_pk_add_f32 v[82:83], v[82:83], v[194:195] op_sel_hi:[1,0] neg_lo:[0,1] neg_hi:[0,1]
	v_pk_add_f32 v[84:85], v[84:85], v[194:195] op_sel_hi:[1,0] neg_lo:[0,1] neg_hi:[0,1]
	v_pk_add_f32 v[86:87], v[86:87], v[194:195] op_sel_hi:[1,0] neg_lo:[0,1] neg_hi:[0,1]
	v_pk_add_f32 v[88:89], v[88:89], v[194:195] op_sel_hi:[1,0] neg_lo:[0,1] neg_hi:[0,1]
	v_pk_add_f32 v[90:91], v[90:91], v[194:195] op_sel_hi:[1,0] neg_lo:[0,1] neg_hi:[0,1]
	v_pk_add_f32 v[92:93], v[92:93], v[194:195] op_sel_hi:[1,0] neg_lo:[0,1] neg_hi:[0,1]
	v_pk_add_f32 v[94:95], v[94:95], v[194:195] op_sel_hi:[1,0] neg_lo:[0,1] neg_hi:[0,1]
	v_exp_f32_e64 v194, -v194
	s_nop 0
	v_mul_f32_e32 v1, v1, v194
	v_pk_mul_f32 v[32:33], v[32:33], v[194:195] op_sel_hi:[1,0]
	v_pk_mul_f32 v[34:35], v[34:35], v[194:195] op_sel_hi:[1,0]
	v_pk_mul_f32 v[36:37], v[36:37], v[194:195] op_sel_hi:[1,0]
	v_pk_mul_f32 v[38:39], v[38:39], v[194:195] op_sel_hi:[1,0]
	v_pk_mul_f32 v[40:41], v[40:41], v[194:195] op_sel_hi:[1,0]
	v_pk_mul_f32 v[42:43], v[42:43], v[194:195] op_sel_hi:[1,0]
	v_pk_mul_f32 v[44:45], v[44:45], v[194:195] op_sel_hi:[1,0]
	v_pk_mul_f32 v[46:47], v[46:47], v[194:195] op_sel_hi:[1,0]
	v_pk_mul_f32 v[16:17], v[16:17], v[194:195] op_sel_hi:[1,0]
	v_pk_mul_f32 v[18:19], v[18:19], v[194:195] op_sel_hi:[1,0]
	v_pk_mul_f32 v[20:21], v[20:21], v[194:195] op_sel_hi:[1,0]
	v_pk_mul_f32 v[22:23], v[22:23], v[194:195] op_sel_hi:[1,0]
	v_pk_mul_f32 v[24:25], v[24:25], v[194:195] op_sel_hi:[1,0]
	v_pk_mul_f32 v[26:27], v[26:27], v[194:195] op_sel_hi:[1,0]
	v_pk_mul_f32 v[28:29], v[28:29], v[194:195] op_sel_hi:[1,0]
	v_pk_mul_f32 v[30:31], v[30:31], v[194:195] op_sel_hi:[1,0]
	v_exp_f32_e32 v80, v80
	v_exp_f32_e32 v81, v81
	v_exp_f32_e32 v82, v82
	v_exp_f32_e32 v83, v83
	v_exp_f32_e32 v84, v84
	v_exp_f32_e32 v85, v85
	v_exp_f32_e32 v86, v86
	v_exp_f32_e32 v87, v87
	v_exp_f32_e32 v88, v88
	v_exp_f32_e32 v89, v89
	v_exp_f32_e32 v90, v90
	v_exp_f32_e32 v91, v91
	v_exp_f32_e32 v92, v92
	v_exp_f32_e32 v93, v93
	v_exp_f32_e32 v94, v94
	v_exp_f32_e32 v95, v95
	s_nop 0
	v_cvt_pk_f16_f32 v228, v80, v81
	v_cvt_pk_f16_f32 v229, v82, v83
	v_cvt_pk_f16_f32 v230, v84, v85
	v_cvt_pk_f16_f32 v231, v86, v87
	v_cvt_pk_f16_f32 v232, v88, v89
	v_cvt_pk_f16_f32 v233, v90, v91
	v_cvt_pk_f16_f32 v234, v92, v93
	v_cvt_pk_f16_f32 v235, v94, v95
	v_pk_add_f32 v[80:81], v[80:81], v[82:83]
	v_pk_add_f32 v[84:85], v[84:85], v[86:87]
	v_pk_add_f32 v[88:89], v[88:89], v[90:91]
	v_pk_add_f32 v[92:93], v[92:93], v[94:95]
	v_pk_add_f32 v[80:81], v[80:81], v[84:85]
	v_pk_add_f32 v[88:89], v[88:89], v[92:93]
	v_pk_add_f32 v[80:81], v[80:81], v[88:89]
	v_add_f32_e32 v80, v80, v81
	s_waitcnt lgkmcnt(0)
	s_branch .Lcont_diff2c_1

; template <int DQ, bool NA, int NQG>
; DI void attn_wg(const half_t* Qp, const half_t* Kp, const half_t* Vp, int q0, bool active, int seg0_start, int seg0_tiles,
;                 int seg1_start, int seg1_tiles, const float* rpb_h, int rq, char* smem, int tid, f16v (&O)[2][NQG]) {
;     ...
;       for (int st = 0; st < 2; ++st) {
;         f16v S[NQG];
; #pragma unroll
;         for (int qg = 0; qg < NQG; ++qg)
; #pragma unroll
;           for (int i = 0; i < 16; ++i) S[qg][i] = 0.f;
; #pragma unroll
;         for (int ks = 0; ks < NKS; ++ks) {
;           const h8 kf = *(const h8*)(ksm + (st * 32) * KSTR + ks * 16);
; #pragma unroll
;           for (int qg = 0; qg < NQG; ++qg) S[qg] = __builtin_amdgcn_mfma_f32_32x32x16_f16(kf, qf[qg][ks], S[qg], 0, 0, 0);
;         }
;         if (masked) {
;           const int cb = st * 32;
;           const int dr = krow - rq + 7;
; #pragma unroll
;           for (int qg = 0; qg < NQG; ++qg) {
;             const int qc = qg * 32 + r;
;             const int cs = min(max(qc - 8, 0), 48);
; #pragma unroll
;             for (int i = 0; i < 16; ++i) {
;               const int c = cb + (i & 3) + 8 * (i >> 2) + 4 * h;
;               const bool valid = (c >= cs) && (c < cs + 16);
;               float bias = 0.f;
;               if (valid) bias = rpb_h[dr * 31 + (c - qc + 15)] * LOG2E;
;               S[qg][i] = valid ? S[qg][i] + bias : -1e30f;
;             }
;           }
;         }
;         h4 vf[2][2][2];
; #pragma unroll
;         for (int dvt = 0; dvt < 2; ++dvt)
; #pragma unroll
;           for (int sx = 0; sx < 2; ++sx)
; #pragma unroll
;             for (int hf = 0; hf < 2; ++hf) vf[dvt][sx][hf] = *(const h4*)(vsm + (dvt * 32) * VSTR + st * 32 + sx * 16 + hf * 8);
; #pragma unroll
;         for (int qg = 0; qg < NQG; ++qg) {
;           h8 P[2];
;           float mx = S[qg][0];
; #pragma unroll
;           for (int i = 1; i < 16; ++i) mx = fmaxf(mx, S[qg][i]);
;           mx = fmaxf(mx, __shfl_xor(mx, 32));
;           if (__builtin_amdgcn_ballot_w64(mx > mrun[qg] + 8.f) != 0ull) {
;             const float mnew = fmaxf(mrun[qg], mx);
;             const float alpha = __builtin_amdgcn_exp2f(mrun[qg] - mnew);
;             lrun[qg] *= alpha;
; #pragma unroll
;             for (int dvt = 0; dvt < 2; ++dvt)
; #pragma unroll
;               for (int i = 0; i < 16; ++i) O[dvt][qg][i] *= alpha;
;             mrun[qg] = mnew;
.Leager_diff2c_3:
	s_nop 7
	v_mfma_f32_32x32x16_f16 v[80:95], v[2:5], v[120:123], v[212:227]
	v_mfma_f32_32x32x16_f16 v[80:95], v[6:9], v[124:127], v[80:95]
	s_nop 15
	s_nop 15
	v_max3_f32 v189, v80, v81, v82
	v_max3_f32 v194, v83, v84, v85
	v_max3_f32 v189, v189, v86, v87
	v_max3_f32 v189, v189, v90, v91
	v_max3_f32 v189, v189, v94, v95
	v_max3_f32 v194, v194, v88, v89
	v_max3_f32 v194, v194, v92, v93
	v_max_f32_e32 v189, v189, v194
	v_mov_b32_e32 v194, v189
	s_nop 1
	v_permlane32_swap_b32_e32 v194, v189
	v_max_f32_e32 v189, v189, v194
	v_max_f32_e32 v194, 0, v189
	s_nop 1
	v_pk_add_f32 v[212:213], v[212:213], v[194:195] op_sel_hi:[1,0] neg_lo:[0,1] neg_hi:[0,1]
	v_pk_add_f32 v[214:215], v[214:215], v[194:195] op_sel_hi:[1,0] neg_lo:[0,1] neg_hi:[0,1]
	v_pk_add_f32 v[216:217], v[216:217], v[194:195] op_sel_hi:[1,0] neg_lo:[0,1] neg_hi:[0,1]
	v_pk_add_f32 v[218:219], v[218:219], v[194:195] op_sel_hi:[1,0] neg_lo:[0,1] neg_hi:[0,1]
	v_pk_add_f32 v[220:221], v[220:221], v[194:195] op_sel_hi:[1,0] neg_lo:[0,1] neg_hi:[0,1]
	v_pk_add_f32 v[222:223], v[222:223], v[194:195] op_sel_hi:[1,0] neg_lo:[0,1] neg_hi:[0,1]
	v_pk_add_f32 v[224:225], v[224:225], v[194:195] op_sel_hi:[1,0] neg_lo:[0,1] neg_hi:[0,1]
	v_pk_add_f32 v[226:227], v[226:227], v[194:195] op_sel_hi:[1,0] neg_lo:[0,1] neg_hi:[0,1]
	v_pk_add_f32 v[80:81], v[80:81], v[194:195] op_sel_hi:[1,0] neg_lo:[0,1] neg_hi:[0,1]
	v_pk_add_f32 v[82:83], v[82:83], v[194:195] op_sel_hi:[1,0] neg_lo:[0,1] neg_hi:[0,1]
	v_pk_add_f32 v[84:85], v[84:85], v[194:195] op_sel_hi:[1,0] neg_lo:[0,1] neg_hi:[0,1]
	v_pk_add_f32 v[86:87], v[86:87], v[194:195] op_sel_hi:[1,0] neg_lo:[0,1] neg_hi:[0,1]
	v_pk_add_f32 v[88:89], v[88:89], v[194:195] op_sel_hi:[1,0] neg_lo:[0,1] neg_hi:[0,1]
	v_pk_add_f32 v[90:91], v[90:91], v[194:195] op_sel_hi:[1,0] neg_lo:[0,1] neg_hi:[0,1]
	v_pk_add_f32 v[92:93], v[92:93], v[194:195] op_sel_hi:[1,0] neg_lo:[0,1] neg_hi:[0,1]
	v_pk_add_f32 v[94:95], v[94:95], v[194:195] op_sel_hi:[1,0] neg_lo:[0,1] neg_hi:[0,1]
	v_exp_f32_e64 v194, -v194
	s_nop 0
	v_mul_f32_e32 v1, v1, v194
	v_pk_mul_f32 v[32:33], v[32:33], v[194:195] op_sel_hi:[1,0]
	v_pk_mul_f32 v[34:35], v[34:35], v[194:195] op_sel_hi:[1,0]
	v_pk_mul_f32 v[36:37], v[36:37], v[194:195] op_sel_hi:[1,0]
	v_pk_mul_f32 v[38:39], v[38:39], v[194:195] op_sel_hi:[1,0]
	v_pk_mul_f32 v[40:41], v[40:41], v[194:195] op_sel_hi:[1,0]
	v_pk_mul_f32 v[42:43], v[42:43], v[194:195] op_sel_hi:[1,0]
	v_pk_mul_f32 v[44:45], v[44:45], v[194:195] op_sel_hi:[1,0]
	v_pk_mul_f32 v[46:47], v[46:47], v[194:195] op_sel_hi:[1,0]
	v_pk_mul_f32 v[16:17], v[16:17], v[194:195] op_sel_hi:[1,0]
	v_pk_mul_f32 v[18:19], v[18:19], v[194:195] op_sel_hi:[1,0]
	v_pk_mul_f32 v[20:21], v[20:21], v[194:195] op_sel_hi:[1,0]
	v_pk_mul_f32 v[22:23], v[22:23], v[194:195] op_sel_hi:[1,0]
	v_pk_mul_f32 v[24:25], v[24:25], v[194:195] op_sel_hi:[1,0]
	v_pk_mul_f32 v[26:27], v[26:27], v[194:195] op_sel_hi:[1,0]
	v_pk_mul_f32 v[28:29], v[28:29], v[194:195] op_sel_hi:[1,0]
	v_pk_mul_f32 v[30:31], v[30:31], v[194:195] op_sel_hi:[1,0]
	v_exp_f32_e32 v80, v80
	v_exp_f32_e32 v81, v81
	v_exp_f32_e32 v82, v82
	v_exp_f32_e32 v83, v83
	v_exp_f32_e32 v84, v84
	v_exp_f32_e32 v85, v85
	v_exp_f32_e32 v86, v86
	v_exp_f32_e32 v87, v87
	v_exp_f32_e32 v88, v88
	v_exp_f32_e32 v89, v89
	v_exp_f32_e32 v90, v90
	v_exp_f32_e32 v91, v91
	v_exp_f32_e32 v92, v92
	v_exp_f32_e32 v93, v93
	v_exp_f32_e32 v94, v94
	v_exp_f32_e32 v95, v95
	s_nop 0
	v_cvt_pk_f16_f32 v228, v80, v81
	v_cvt_pk_f16_f32 v229, v82, v83
	v_cvt_pk_f16_f32 v230, v84, v85
	v_cvt_pk_f16_f32 v231, v86, v87
	v_cvt_pk_f16_f32 v232, v88, v89
	v_cvt_pk_f16_f32 v233, v90, v91
	v_cvt_pk_f16_f32 v234, v92, v93
	v_cvt_pk_f16_f32 v235, v94, v95
	v_pk_add_f32 v[80:81], v[80:81], v[82:83]
	v_pk_add_f32 v[84:85], v[84:85], v[86:87]
	v_pk_add_f32 v[88:89], v[88:89], v[90:91]
	v_pk_add_f32 v[92:93], v[92:93], v[94:95]
	v_pk_add_f32 v[80:81], v[80:81], v[84:85]
	v_pk_add_f32 v[88:89], v[88:89], v[92:93]
	v_pk_add_f32 v[80:81], v[80:81], v[88:89]
	v_add_f32_e32 v80, v80, v81
	s_branch .Lcont_diff2c_3
